# attention loop: PV fragment reads double-buffered, next-tile LDS staging writes and following global loads issued before the last PV MFMA group; s5 scan recurrence as 2-deep fma chain
# speedup vs baseline: 1.0108x; 1.0093x over previous
.LBB0_696:
	v_cvt_pk_bf16_f32 v0, v0, v1
	v_cvt_pk_bf16_f32 v1, v2, v3
	v_cvt_pk_bf16_f32 v2, v4, v5
	v_cvt_pk_bf16_f32 v3, v6, v7
	v_cvt_pk_bf16_f32 v4, v8, v9
	v_cvt_pk_bf16_f32 v5, v10, v11
	v_cvt_pk_bf16_f32 v6, v12, v13
	v_cvt_pk_bf16_f32 v7, v14, v15
	v_cvt_pk_bf16_f32 v8, v16, v17
	v_cvt_pk_bf16_f32 v9, v18, v19
	v_cvt_pk_bf16_f32 v10, v20, v21
	v_cvt_pk_bf16_f32 v11, v22, v23
	v_cvt_pk_bf16_f32 v12, v24, v25
	v_cvt_pk_bf16_f32 v13, v26, v27
	ds_write2_b64 v204, v[0:1], v[2:3] offset1:2
	ds_write2_b64 v204, v[4:5], v[6:7] offset0:4 offset1:6
	ds_write2_b64 v204, v[8:9], v[10:11] offset0:8 offset1:10
	v_cvt_pk_bf16_f32 v0, v28, v29
	v_cvt_pk_bf16_f32 v1, v30, v31
	ds_write2_b64 v204, v[12:13], v[0:1] offset0:12 offset1:14
	s_addk_i32 s23, 0x4400
	v_add_u32_e32 v242, s23, v199
	ds_read_b128 v[0:3], v205
	ds_read_b64_tr_b16 v[16:17], v242 offset:0
	ds_read_b64_tr_b16 v[18:19], v242 offset:1088
	ds_read_b64_tr_b16 v[12:13], v242 offset:64
	ds_read_b64_tr_b16 v[14:15], v242 offset:1152
	ds_read_b64_tr_b16 v[8:9], v242 offset:128
	ds_read_b64_tr_b16 v[10:11], v242 offset:1216
	ds_read_b64_tr_b16 v[4:5], v242 offset:192
	ds_read_b64_tr_b16 v[6:7], v242 offset:1280
	v_add_u32_e32 v243, s23, v200
	ds_read_b128 v[20:23], v205 offset:32
	ds_read_b64_tr_b16 v[24:25], v243 offset:0
	ds_read_b64_tr_b16 v[26:27], v243 offset:1088
	ds_read_b64_tr_b16 v[28:29], v243 offset:64
	ds_read_b64_tr_b16 v[30:31], v243 offset:1152
	ds_read_b64_tr_b16 v[234:235], v243 offset:128
	ds_read_b64_tr_b16 v[236:237], v243 offset:1216
	ds_read_b64_tr_b16 v[238:239], v243 offset:192
	ds_read_b64_tr_b16 v[240:241], v243 offset:1280
	s_mov_b64 s[8:9], -1
	s_waitcnt lgkmcnt(9)
	v_mfma_f32_32x32x16_bf16 v[82:97], v[0:3], v[16:19], v[82:97]
	v_mfma_f32_32x32x16_bf16 v[66:81], v[0:3], v[12:15], v[66:81]
	v_mfma_f32_32x32x16_bf16 v[50:65], v[0:3], v[8:11], v[50:65]
	v_mfma_f32_32x32x16_bf16 v[34:49], v[0:3], v[4:7], v[34:49]
	v_add_u32_e32 v242, s23, v201
	ds_read_b128 v[0:3], v205 offset:64
	ds_read_b64_tr_b16 v[16:17], v242 offset:0
	ds_read_b64_tr_b16 v[18:19], v242 offset:1088
	ds_read_b64_tr_b16 v[12:13], v242 offset:64
	ds_read_b64_tr_b16 v[14:15], v242 offset:1152
	ds_read_b64_tr_b16 v[8:9], v242 offset:128
	ds_read_b64_tr_b16 v[10:11], v242 offset:1216
	ds_read_b64_tr_b16 v[4:5], v242 offset:192
	ds_read_b64_tr_b16 v[6:7], v242 offset:1280
	s_waitcnt lgkmcnt(9)
	v_mfma_f32_32x32x16_bf16 v[82:97], v[20:23], v[24:27], v[82:97]
	v_mfma_f32_32x32x16_bf16 v[66:81], v[20:23], v[28:31], v[66:81]
	v_mfma_f32_32x32x16_bf16 v[50:65], v[20:23], v[234:237], v[50:65]
	v_mfma_f32_32x32x16_bf16 v[34:49], v[20:23], v[238:241], v[34:49]
	v_add_u32_e32 v243, s23, v202
	ds_read_b128 v[20:23], v205 offset:96
	ds_read_b64_tr_b16 v[24:25], v243 offset:0
	ds_read_b64_tr_b16 v[26:27], v243 offset:1088
	ds_read_b64_tr_b16 v[28:29], v243 offset:64
	ds_read_b64_tr_b16 v[30:31], v243 offset:1152
	ds_read_b64_tr_b16 v[234:235], v243 offset:128
	ds_read_b64_tr_b16 v[236:237], v243 offset:1216
	ds_read_b64_tr_b16 v[238:239], v243 offset:192
	ds_read_b64_tr_b16 v[240:241], v243 offset:1280
	s_waitcnt lgkmcnt(9)
	v_mfma_f32_32x32x16_bf16 v[82:97], v[0:3], v[16:19], v[82:97]
	v_mfma_f32_32x32x16_bf16 v[66:81], v[0:3], v[12:15], v[66:81]
	v_mfma_f32_32x32x16_bf16 v[50:65], v[0:3], v[8:11], v[50:65]
	v_mfma_f32_32x32x16_bf16 v[34:49], v[0:3], v[4:7], v[34:49]
	s_cmp_lt_i32 s17, s15
	s_cbranch_scc0 .Lattn_nostage
	s_add_i32 s23, s16, 1
	s_bitcmp1_b32 s23, 0
	s_cselect_b32 s23, 0x8800, 0
	v_add_u32_e32 v244, s23, v171
	s_waitcnt vmcnt(3)
	ds_write_b128 v244, v[130:133]
	s_waitcnt vmcnt(2)
	ds_write_b128 v244, v[134:137] offset:17408
	s_waitcnt vmcnt(1)
	ds_write_b128 v244, v[138:141] offset:8704
	s_waitcnt vmcnt(0)
	ds_write_b128 v244, v[142:145] offset:26112
	s_add_i32 s23, s17, 1
	s_cmp_ge_i32 s23, s15
	s_cbranch_scc1 .Lattn_noload
	v_add_co_u32_e32 v244, vcc, 0xfffa8000, v162
	s_nop 1
	v_addc_co_u32_e32 v245, vcc, -1, v163, vcc
	global_load_dwordx4 v[130:133], v[244:245], off offset:-512
	global_load_dwordx4 v[134:137], v[244:245], off
	global_load_dwordx4 v[138:141], v[162:163], off offset:-512
	global_load_dwordx4 v[142:145], v[162:163], off
.Lattn_noload:
	s_waitcnt lgkmcnt(4)
	s_branch .Lattn_stage_done

.Lattn_stage_done:
	v_mfma_f32_32x32x16_bf16 v[82:97], v[20:23], v[24:27], v[82:97]
	v_mfma_f32_32x32x16_bf16 v[66:81], v[20:23], v[28:31], v[66:81]
	v_mfma_f32_32x32x16_bf16 v[50:65], v[20:23], v[234:237], v[50:65]
	v_mfma_f32_32x32x16_bf16 v[34:49], v[20:23], v[238:241], v[34:49]
	s_cmp_lt_i32 s17, s15
	s_cbranch_scc1 .LBB0_698
	s_add_i32 s23, s16, 1
	s_mov_b64 s[8:9], 0
.LBB0_698:
	s_andn2_b64 vcc, exec, s[8:9]
	s_cbranch_vccnz .LBB0_701
	s_add_i32 s17, s17, 1
	s_add_i32 s16, s16, 1
	s_branch .LBB0_702

.Ls5_scan:
	s_waitcnt lgkmcnt(14)
	ds_write2st64_b32 v40, v38, v39 offset1:1
	v_fma_f32 v36, -v35, v39, v80
	v_fma_f32 v37, v35, v38, v81
	v_fma_f32 v38, v34, v38, v36
	v_fma_f32 v39, v34, v39, v37
	v_add_u32_e32 v40, s24, v40
	ds_read2st64_b32 v[80:81], v40 offset1:1
	s_waitcnt lgkmcnt(14)
	ds_write2st64_b32 v41, v38, v39 offset1:1
	v_fma_f32 v36, -v35, v39, v82
	v_fma_f32 v37, v35, v38, v83
	v_fma_f32 v38, v34, v38, v36
	v_fma_f32 v39, v34, v39, v37
	v_add_u32_e32 v41, s24, v41
	ds_read2st64_b32 v[82:83], v41 offset1:1
	s_waitcnt lgkmcnt(14)
	ds_write2st64_b32 v42, v38, v39 offset1:1
	v_fma_f32 v36, -v35, v39, v84
	v_fma_f32 v37, v35, v38, v85
	v_fma_f32 v38, v34, v38, v36
	v_fma_f32 v39, v34, v39, v37
	v_add_u32_e32 v42, s24, v42
	ds_read2st64_b32 v[84:85], v42 offset1:1
	s_waitcnt lgkmcnt(14)
	ds_write2st64_b32 v43, v38, v39 offset1:1
	v_fma_f32 v36, -v35, v39, v86
	v_fma_f32 v37, v35, v38, v87
	v_fma_f32 v38, v34, v38, v36
	v_fma_f32 v39, v34, v39, v37
	v_add_u32_e32 v43, s24, v43
	ds_read2st64_b32 v[86:87], v43 offset1:1
	s_waitcnt lgkmcnt(14)
	ds_write2st64_b32 v44, v38, v39 offset1:1
	v_fma_f32 v36, -v35, v39, v88
	v_fma_f32 v37, v35, v38, v89
	v_fma_f32 v38, v34, v38, v36
	v_fma_f32 v39, v34, v39, v37
	v_add_u32_e32 v44, s24, v44
	ds_read2st64_b32 v[88:89], v44 offset1:1
	s_waitcnt lgkmcnt(14)
	ds_write2st64_b32 v45, v38, v39 offset1:1
	v_fma_f32 v36, -v35, v39, v90
	v_fma_f32 v37, v35, v38, v91
	v_fma_f32 v38, v34, v38, v36
	v_fma_f32 v39, v34, v39, v37
	v_add_u32_e32 v45, s24, v45
	ds_read2st64_b32 v[90:91], v45 offset1:1
	s_waitcnt lgkmcnt(14)
	ds_write2st64_b32 v46, v38, v39 offset1:1
	v_fma_f32 v36, -v35, v39, v92
	v_fma_f32 v37, v35, v38, v93
	v_fma_f32 v38, v34, v38, v36
	v_fma_f32 v39, v34, v39, v37
	v_add_u32_e32 v46, s24, v46
	ds_read2st64_b32 v[92:93], v46 offset1:1
	s_waitcnt lgkmcnt(14)
	ds_write2st64_b32 v47, v38, v39 offset1:1
	v_fma_f32 v36, -v35, v39, v94
	v_fma_f32 v37, v35, v38, v95
	v_fma_f32 v38, v34, v38, v36
	v_fma_f32 v39, v34, v39, v37
	v_add_u32_e32 v47, s24, v47
	ds_read2st64_b32 v[94:95], v47 offset1:1
	s_add_i32 s7, s7, -1
	s_cmp_lg_u32 s7, 0
	s_cbranch_scc1 .Ls5_scan
